# PE fourier-map K-loop: prioritized hand-off (post-MFMA barrier 2 MFMAs early at s_setprio 2), as in the other GEMM loops
# speedup vs baseline: 1.0051x; 1.0017x over previous
.LBB0_841:
	s_add_u32 s28, s26, 0x100
	s_addc_u32 s29, s27, 0
	s_add_i32 s38, 0, 0x10000
	s_cmp_eq_u32 s81, 14
	s_cselect_b32 s35, s23, s29
	s_cselect_b32 s34, s22, s28
	s_cselect_b32 s31, s25, s80
	s_cselect_b32 s30, s24, s79
	s_add_i32 s39, 0, 0x14000
	v_add_u32_e32 v152, s38, v146
	v_add_u32_e32 v168, s39, v146
	ds_read_b128 v[138:141], v152
	ds_read_b128 v[142:145], v152 offset:1024
	ds_read_b128 v[148:151], v152 offset:2048
	ds_read_b128 v[152:155], v152 offset:3072
	ds_read_b128 v[156:159], v168
	ds_read_b128 v[160:163], v168 offset:1024
	ds_read_b128 v[164:167], v168 offset:2048
	ds_read_b128 v[168:171], v168 offset:3072
	s_add_i32 m0, s50, 0xc000
	ds_read_b128 v[172:175], v147
	ds_read_b128 v[178:181], v147 offset:1024
	ds_read_b128 v[182:185], v147 offset:2048
	ds_read_b128 v[188:191], v147 offset:3072
	ds_read_b128 v[192:195], v147 offset:4096
	ds_read_b128 v[196:199], v147 offset:5120
	ds_read_b128 v[200:203], v147 offset:6144
	ds_read_b128 v[204:207], v147 offset:7168
	global_load_lds_dwordx4 v134, s[26:27]
	s_add_i32 m0, s50, 0xe000
	s_nop 0
	global_load_lds_dwordx4 v136, s[26:27]
	s_waitcnt vmcnt(8)
	s_waitcnt lgkmcnt(0)
	s_barrier
	s_setprio 1
	s_waitcnt lgkmcnt(0)
	v_mfma_f32_16x16x32_bf16 v[124:127], v[138:141], v[172:175], v[124:127]
	v_mfma_f32_16x16x32_bf16 v[120:123], v[148:151], v[172:175], v[120:123]
	v_mfma_f32_16x16x32_bf16 v[108:111], v[138:141], v[182:185], v[108:111]
	v_mfma_f32_16x16x32_bf16 v[104:107], v[148:151], v[182:185], v[104:107]
	v_mfma_f32_16x16x32_bf16 v[92:95], v[138:141], v[192:195], v[92:95]
	v_mfma_f32_16x16x32_bf16 v[88:91], v[148:151], v[192:195], v[88:91]
	v_mfma_f32_16x16x32_bf16 v[76:79], v[138:141], v[200:203], v[76:79]
	v_mfma_f32_16x16x32_bf16 v[72:75], v[148:151], v[200:203], v[72:75]
	v_mfma_f32_16x16x32_bf16 v[124:127], v[142:145], v[178:181], v[124:127]
	v_mfma_f32_16x16x32_bf16 v[120:123], v[152:155], v[178:181], v[120:123]
	v_mfma_f32_16x16x32_bf16 v[108:111], v[142:145], v[188:191], v[108:111]
	v_mfma_f32_16x16x32_bf16 v[104:107], v[152:155], v[188:191], v[104:107]
	v_mfma_f32_16x16x32_bf16 v[92:95], v[142:145], v[196:199], v[92:95]
	v_mfma_f32_16x16x32_bf16 v[88:91], v[152:155], v[196:199], v[88:91]
	v_mfma_f32_16x16x32_bf16 v[76:79], v[142:145], v[204:207], v[76:79]
	v_mfma_f32_16x16x32_bf16 v[72:75], v[152:155], v[204:207], v[72:75]
	s_setprio 0
	s_setprio 1
	v_mfma_f32_16x16x32_bf16 v[116:119], v[156:159], v[172:175], v[116:119]
	v_mfma_f32_16x16x32_bf16 v[112:115], v[164:167], v[172:175], v[112:115]
	v_mfma_f32_16x16x32_bf16 v[100:103], v[156:159], v[182:185], v[100:103]
	v_mfma_f32_16x16x32_bf16 v[96:99], v[164:167], v[182:185], v[96:99]
	v_mfma_f32_16x16x32_bf16 v[84:87], v[156:159], v[192:195], v[84:87]
	v_mfma_f32_16x16x32_bf16 v[80:83], v[164:167], v[192:195], v[80:83]
	v_mfma_f32_16x16x32_bf16 v[68:71], v[156:159], v[200:203], v[68:71]
	v_mfma_f32_16x16x32_bf16 v[64:67], v[164:167], v[200:203], v[64:67]
	v_mfma_f32_16x16x32_bf16 v[116:119], v[160:163], v[178:181], v[116:119]
	v_mfma_f32_16x16x32_bf16 v[112:115], v[168:171], v[178:181], v[112:115]
	v_mfma_f32_16x16x32_bf16 v[100:103], v[160:163], v[188:191], v[100:103]
	v_mfma_f32_16x16x32_bf16 v[96:99], v[168:171], v[188:191], v[96:99]
	v_mfma_f32_16x16x32_bf16 v[84:87], v[160:163], v[196:199], v[84:87]
	v_mfma_f32_16x16x32_bf16 v[80:83], v[168:171], v[196:199], v[80:83]
	s_setprio 2
	s_barrier
	v_mfma_f32_16x16x32_bf16 v[68:71], v[160:163], v[204:207], v[68:71]
	v_mfma_f32_16x16x32_bf16 v[64:67], v[168:171], v[204:207], v[64:67]
	s_setprio 0
	s_add_i32 s26, s38, s49
	s_add_u32 s90, s30, 0x80
	s_addc_u32 s91, s31, 0
	s_mov_b32 m0, s26
	ds_read_b128 v[172:175], v147 offset:16384
	ds_read_b128 v[178:181], v147 offset:17408
	ds_read_b128 v[182:185], v147 offset:18432
	ds_read_b128 v[188:191], v147 offset:19456
	ds_read_b128 v[192:195], v147 offset:20480
	ds_read_b128 v[196:199], v147 offset:21504
	ds_read_b128 v[200:203], v147 offset:22528
	ds_read_b128 v[204:207], v147 offset:23552
	global_load_lds_dwordx4 v176, s[30:31]
	s_add_i32 m0, s26, 0x2000
	s_add_u32 s26, s30, 0x48000
	s_addc_u32 s27, s31, 0
	s_add_i32 s38, s39, s49
	global_load_lds_dwordx4 v132, s[30:31]
	s_mov_b32 m0, s38
	s_nop 0
	global_load_lds_dwordx4 v176, s[26:27]
	s_add_i32 m0, s38, 0x2000
	s_nop 0
	global_load_lds_dwordx4 v132, s[26:27]
	s_add_u32 s96, s34, 0x80
	s_addc_u32 s97, s35, 0
	s_mov_b32 m0, s50
	s_nop 0
	global_load_lds_dwordx4 v128, s[34:35]
	s_mov_b32 m0, s51
	s_nop 0
	global_load_lds_dwordx4 v130, s[34:35]
	s_waitcnt vmcnt(8)
	s_waitcnt lgkmcnt(0)
	s_barrier
	s_setprio 1
	s_waitcnt lgkmcnt(0)
	v_mfma_f32_16x16x32_bf16 v[60:63], v[138:141], v[172:175], v[60:63]
	v_mfma_f32_16x16x32_bf16 v[56:59], v[148:151], v[172:175], v[56:59]
	v_mfma_f32_16x16x32_bf16 v[44:47], v[138:141], v[182:185], v[44:47]
	v_mfma_f32_16x16x32_bf16 v[40:43], v[148:151], v[182:185], v[40:43]
	v_mfma_f32_16x16x32_bf16 v[28:31], v[138:141], v[192:195], v[28:31]
	v_mfma_f32_16x16x32_bf16 v[24:27], v[148:151], v[192:195], v[24:27]
	v_mfma_f32_16x16x32_bf16 v[12:15], v[138:141], v[200:203], v[12:15]
	v_mfma_f32_16x16x32_bf16 v[8:11], v[148:151], v[200:203], v[8:11]
	v_mfma_f32_16x16x32_bf16 v[60:63], v[142:145], v[178:181], v[60:63]
	v_mfma_f32_16x16x32_bf16 v[56:59], v[152:155], v[178:181], v[56:59]
	v_mfma_f32_16x16x32_bf16 v[44:47], v[142:145], v[188:191], v[44:47]
	v_mfma_f32_16x16x32_bf16 v[40:43], v[152:155], v[188:191], v[40:43]
	v_mfma_f32_16x16x32_bf16 v[28:31], v[142:145], v[196:199], v[28:31]
	v_mfma_f32_16x16x32_bf16 v[24:27], v[152:155], v[196:199], v[24:27]
	v_mfma_f32_16x16x32_bf16 v[12:15], v[142:145], v[204:207], v[12:15]
	v_mfma_f32_16x16x32_bf16 v[8:11], v[152:155], v[204:207], v[8:11]
	s_setprio 0
	s_setprio 1
	v_mfma_f32_16x16x32_bf16 v[52:55], v[156:159], v[172:175], v[52:55]
	v_mfma_f32_16x16x32_bf16 v[48:51], v[164:167], v[172:175], v[48:51]
	v_mfma_f32_16x16x32_bf16 v[36:39], v[156:159], v[182:185], v[36:39]
	v_mfma_f32_16x16x32_bf16 v[32:35], v[164:167], v[182:185], v[32:35]
	v_mfma_f32_16x16x32_bf16 v[20:23], v[156:159], v[192:195], v[20:23]
	v_mfma_f32_16x16x32_bf16 v[16:19], v[164:167], v[192:195], v[16:19]
	v_mfma_f32_16x16x32_bf16 v[4:7], v[156:159], v[200:203], v[4:7]
	v_mfma_f32_16x16x32_bf16 v[0:3], v[164:167], v[200:203], v[0:3]
	v_mfma_f32_16x16x32_bf16 v[52:55], v[160:163], v[178:181], v[52:55]
	v_mfma_f32_16x16x32_bf16 v[48:51], v[168:171], v[178:181], v[48:51]
	v_mfma_f32_16x16x32_bf16 v[36:39], v[160:163], v[188:191], v[36:39]
	v_mfma_f32_16x16x32_bf16 v[32:35], v[168:171], v[188:191], v[32:35]
	v_mfma_f32_16x16x32_bf16 v[20:23], v[160:163], v[196:199], v[20:23]
	v_mfma_f32_16x16x32_bf16 v[16:19], v[168:171], v[196:199], v[16:19]
	s_setprio 2
	s_barrier
	v_mfma_f32_16x16x32_bf16 v[4:7], v[160:163], v[204:207], v[4:7]
	v_mfma_f32_16x16x32_bf16 v[0:3], v[168:171], v[204:207], v[0:3]
	s_setprio 0
	s_add_i32 s38, 0, 0x18000
	s_add_i32 s39, 0, 0x1c000
	v_add_u32_e32 v152, s38, v146
	v_add_u32_e32 v168, s39, v146
	ds_read_b128 v[138:141], v152
	ds_read_b128 v[142:145], v152 offset:1024
	ds_read_b128 v[148:151], v152 offset:2048
	ds_read_b128 v[152:155], v152 offset:3072
	ds_read_b128 v[156:159], v168
	ds_read_b128 v[160:163], v168 offset:1024
	ds_read_b128 v[164:167], v168 offset:2048
	ds_read_b128 v[168:171], v168 offset:3072
	s_add_u32 s26, s34, 0x48000
	s_addc_u32 s27, s35, 0
	s_mov_b32 m0, s52
	ds_read_b128 v[172:175], v147 offset:32768
	ds_read_b128 v[178:181], v147 offset:33792
	ds_read_b128 v[182:185], v147 offset:34816
	ds_read_b128 v[188:191], v147 offset:35840
	ds_read_b128 v[192:195], v147 offset:36864
	ds_read_b128 v[196:199], v147 offset:37888
	ds_read_b128 v[200:203], v147 offset:38912
	ds_read_b128 v[204:207], v147 offset:39936
	global_load_lds_dwordx4 v128, s[26:27]
	s_mov_b32 m0, s56
	s_nop 0
	global_load_lds_dwordx4 v130, s[26:27]
	s_waitcnt vmcnt(8)
	s_waitcnt lgkmcnt(0)
	s_barrier
	s_setprio 1
	s_waitcnt lgkmcnt(0)
	v_mfma_f32_16x16x32_bf16 v[124:127], v[138:141], v[172:175], v[124:127]
	v_mfma_f32_16x16x32_bf16 v[120:123], v[148:151], v[172:175], v[120:123]
	v_mfma_f32_16x16x32_bf16 v[108:111], v[138:141], v[182:185], v[108:111]
	v_mfma_f32_16x16x32_bf16 v[104:107], v[148:151], v[182:185], v[104:107]
	v_mfma_f32_16x16x32_bf16 v[92:95], v[138:141], v[192:195], v[92:95]
	v_mfma_f32_16x16x32_bf16 v[88:91], v[148:151], v[192:195], v[88:91]
	v_mfma_f32_16x16x32_bf16 v[76:79], v[138:141], v[200:203], v[76:79]
	v_mfma_f32_16x16x32_bf16 v[72:75], v[148:151], v[200:203], v[72:75]
	v_mfma_f32_16x16x32_bf16 v[124:127], v[142:145], v[178:181], v[124:127]
	v_mfma_f32_16x16x32_bf16 v[120:123], v[152:155], v[178:181], v[120:123]
	v_mfma_f32_16x16x32_bf16 v[108:111], v[142:145], v[188:191], v[108:111]
	v_mfma_f32_16x16x32_bf16 v[104:107], v[152:155], v[188:191], v[104:107]
	v_mfma_f32_16x16x32_bf16 v[92:95], v[142:145], v[196:199], v[92:95]
	v_mfma_f32_16x16x32_bf16 v[88:91], v[152:155], v[196:199], v[88:91]
	v_mfma_f32_16x16x32_bf16 v[76:79], v[142:145], v[204:207], v[76:79]
	v_mfma_f32_16x16x32_bf16 v[72:75], v[152:155], v[204:207], v[72:75]
	s_setprio 0
	s_setprio 1
	v_mfma_f32_16x16x32_bf16 v[116:119], v[156:159], v[172:175], v[116:119]
	v_mfma_f32_16x16x32_bf16 v[112:115], v[164:167], v[172:175], v[112:115]
	v_mfma_f32_16x16x32_bf16 v[100:103], v[156:159], v[182:185], v[100:103]
	v_mfma_f32_16x16x32_bf16 v[96:99], v[164:167], v[182:185], v[96:99]
	v_mfma_f32_16x16x32_bf16 v[84:87], v[156:159], v[192:195], v[84:87]
	v_mfma_f32_16x16x32_bf16 v[80:83], v[164:167], v[192:195], v[80:83]
	v_mfma_f32_16x16x32_bf16 v[68:71], v[156:159], v[200:203], v[68:71]
	v_mfma_f32_16x16x32_bf16 v[64:67], v[164:167], v[200:203], v[64:67]
	v_mfma_f32_16x16x32_bf16 v[116:119], v[160:163], v[178:181], v[116:119]
	v_mfma_f32_16x16x32_bf16 v[112:115], v[168:171], v[178:181], v[112:115]
	v_mfma_f32_16x16x32_bf16 v[100:103], v[160:163], v[188:191], v[100:103]
	v_mfma_f32_16x16x32_bf16 v[96:99], v[168:171], v[188:191], v[96:99]
	v_mfma_f32_16x16x32_bf16 v[84:87], v[160:163], v[196:199], v[84:87]
	v_mfma_f32_16x16x32_bf16 v[80:83], v[168:171], v[196:199], v[80:83]
	s_setprio 2
	s_barrier
	v_mfma_f32_16x16x32_bf16 v[68:71], v[160:163], v[204:207], v[68:71]
	v_mfma_f32_16x16x32_bf16 v[64:67], v[168:171], v[204:207], v[64:67]
	s_setprio 0
	s_add_i32 s26, s38, s49
	s_mov_b32 m0, s26
	ds_read_b128 v[172:175], v147 offset:49152
	ds_read_b128 v[178:181], v147 offset:50176
	ds_read_b128 v[182:185], v147 offset:51200
	ds_read_b128 v[188:191], v147 offset:52224
	ds_read_b128 v[192:195], v147 offset:53248
	ds_read_b128 v[196:199], v147 offset:54272
	ds_read_b128 v[200:203], v147 offset:55296
	ds_read_b128 v[204:207], v147 offset:56320
	global_load_lds_dwordx4 v176, s[90:91]
	s_add_i32 m0, s26, 0x2000
	s_add_u32 s26, s30, 0x48080
	s_addc_u32 s27, s31, 0
	s_add_i32 s30, s39, s49
	global_load_lds_dwordx4 v132, s[90:91]
	s_mov_b32 m0, s30
	s_nop 0
	global_load_lds_dwordx4 v176, s[26:27]
	s_add_i32 m0, s30, 0x2000
	s_nop 0
	global_load_lds_dwordx4 v132, s[26:27]
	s_mov_b32 m0, s57
	s_nop 0
	global_load_lds_dwordx4 v128, s[96:97]
	s_mov_b32 m0, s85
	s_nop 0
	global_load_lds_dwordx4 v130, s[96:97]
	s_waitcnt vmcnt(8)
	s_waitcnt lgkmcnt(0)
	s_barrier
	s_setprio 1
	s_waitcnt lgkmcnt(0)
	v_mfma_f32_16x16x32_bf16 v[60:63], v[138:141], v[172:175], v[60:63]
	v_mfma_f32_16x16x32_bf16 v[56:59], v[148:151], v[172:175], v[56:59]
	v_mfma_f32_16x16x32_bf16 v[44:47], v[138:141], v[182:185], v[44:47]
	v_mfma_f32_16x16x32_bf16 v[40:43], v[148:151], v[182:185], v[40:43]
	v_mfma_f32_16x16x32_bf16 v[28:31], v[138:141], v[192:195], v[28:31]
	v_mfma_f32_16x16x32_bf16 v[24:27], v[148:151], v[192:195], v[24:27]
	v_mfma_f32_16x16x32_bf16 v[12:15], v[138:141], v[200:203], v[12:15]
	v_mfma_f32_16x16x32_bf16 v[8:11], v[148:151], v[200:203], v[8:11]
	v_mfma_f32_16x16x32_bf16 v[60:63], v[142:145], v[178:181], v[60:63]
	v_mfma_f32_16x16x32_bf16 v[56:59], v[152:155], v[178:181], v[56:59]
	v_mfma_f32_16x16x32_bf16 v[44:47], v[142:145], v[188:191], v[44:47]
	v_mfma_f32_16x16x32_bf16 v[40:43], v[152:155], v[188:191], v[40:43]
	v_mfma_f32_16x16x32_bf16 v[28:31], v[142:145], v[196:199], v[28:31]
	v_mfma_f32_16x16x32_bf16 v[24:27], v[152:155], v[196:199], v[24:27]
	v_mfma_f32_16x16x32_bf16 v[12:15], v[142:145], v[204:207], v[12:15]
	v_mfma_f32_16x16x32_bf16 v[8:11], v[152:155], v[204:207], v[8:11]
	s_setprio 0
	s_setprio 1
	v_mfma_f32_16x16x32_bf16 v[52:55], v[156:159], v[172:175], v[52:55]
	v_mfma_f32_16x16x32_bf16 v[48:51], v[164:167], v[172:175], v[48:51]
	v_mfma_f32_16x16x32_bf16 v[36:39], v[156:159], v[182:185], v[36:39]
	v_mfma_f32_16x16x32_bf16 v[32:35], v[164:167], v[182:185], v[32:35]
	v_mfma_f32_16x16x32_bf16 v[20:23], v[156:159], v[192:195], v[20:23]
	v_mfma_f32_16x16x32_bf16 v[16:19], v[164:167], v[192:195], v[16:19]
	v_mfma_f32_16x16x32_bf16 v[4:7], v[156:159], v[200:203], v[4:7]
	v_mfma_f32_16x16x32_bf16 v[0:3], v[164:167], v[200:203], v[0:3]
	v_mfma_f32_16x16x32_bf16 v[52:55], v[160:163], v[178:181], v[52:55]
	v_mfma_f32_16x16x32_bf16 v[48:51], v[168:171], v[178:181], v[48:51]
	v_mfma_f32_16x16x32_bf16 v[36:39], v[160:163], v[188:191], v[36:39]
	v_mfma_f32_16x16x32_bf16 v[32:35], v[168:171], v[188:191], v[32:35]
	v_mfma_f32_16x16x32_bf16 v[20:23], v[160:163], v[196:199], v[20:23]
	v_mfma_f32_16x16x32_bf16 v[16:19], v[168:171], v[196:199], v[16:19]
	s_setprio 2
	s_barrier
	v_mfma_f32_16x16x32_bf16 v[4:7], v[160:163], v[204:207], v[4:7]
	v_mfma_f32_16x16x32_bf16 v[0:3], v[168:171], v[204:207], v[0:3]
	s_setprio 0
	s_add_i32 s81, s81, 2
	s_add_u32 s79, s79, 0x100
	s_addc_u32 s80, s80, 0
	s_cmp_gt_u32 s81, 15
	s_mov_b64 s[26:27], s[28:29]
	s_cbranch_scc0 .LBB0_841
	s_and_b64 vcc, exec, s[20:21]
	s_cbranch_vccz .LBB0_844
	s_barrier
